# one static s_setprio 1 at kernel entry for waves 4-7 (the kernel has no other priority changes)
# baseline (speedup 1.0000x reference)
_Z9trunk_fwd4Args:
	v_readfirstlane_b32 vcc_lo, v0
	s_nop 3
	s_and_b32 vcc_lo, vcc_lo, 0x3ff
	s_lshr_b32 vcc_lo, vcc_lo, 8
	s_cmp_eq_u32 vcc_lo, 1
	s_cbranch_scc0 .Lprio_done
	s_setprio 1
.Lprio_done:
	s_load_dwordx2 s[4:5], s[0:1], 0xc0
	s_load_dwordx2 s[8:9], s[0:1], 0xd0
	s_add_u32 s6, s0, 0xd0
	s_addc_u32 s7, s1, 0
	s_mov_b32 s54, s2
	s_waitcnt lgkmcnt(0)
	s_add_u32 s10, s4, 0xa400000
	v_writelane_b32 v250, s4, 0
	s_addc_u32 s11, s5, 0
	s_cmpk_eq_i32 s8, 0x100
	v_writelane_b32 v250, s5, 1
	s_cselect_b64 s[4:5], -1, 0
	v_writelane_b32 v250, s4, 2
	s_cmpk_lg_i32 s8, 0x100
	s_mov_b64 s[56:57], s[8:9]
	v_writelane_b32 v250, s5, 3
	s_cselect_b64 s[4:5], -1, 0
	v_writelane_b32 v250, s4, 4
	s_and_b32 s33, s2, 7
	s_and_b64 vcc, exec, s[4:5]
	v_writelane_b32 v250, s5, 5
	v_writelane_b32 v250, s10, 6
	s_nop 1
	v_writelane_b32 v250, s11, 7
	v_writelane_b32 v250, s10, 8
	s_nop 1
	v_writelane_b32 v250, s11, 9
	s_cbranch_vccnz .LBB0_2
	s_mul_i32 s2, s33, 0x1400000
	v_readlane_b32 s4, v250, 6
	v_readlane_b32 s5, v250, 7
	s_add_u32 s2, s4, s2
	s_addc_u32 s3, s5, 0
	v_writelane_b32 v250, s2, 8
	s_nop 1
	v_writelane_b32 v250, s3, 9
